# v9 + grid barrier: all workgroups wait on the cross-XCD arrival counter (no TOPGEN/XGEN hops)
# baseline (speedup 1.0000x reference)
; __device__ __forceinline__ unsigned xb_ld(unsigned* p)              { return __hip_atomic_load(p, __ATOMIC_RELAXED, __HIP_MEMORY_SCOPE_AGENT); }
; __device__ __forceinline__ unsigned xb_add(unsigned* p, unsigned v) { return __hip_atomic_fetch_add(p, v, __ATOMIC_RELAXED, __HIP_MEMORY_SCOPE_AGENT); }
; #define XB_SPIN(cond, bar) do { unsigned _sp = 0; while (cond) { __builtin_amdgcn_s_sleep(1); \
;     if ((++_sp & 255u) == 0u) { if (xb_ld(&(bar)[XB_TMO])) break; if (_sp > XB_SPIN_CAP) { atomicAdd(&(bar)[XB_TMO], 1u); break; } } } } while (0)
; __device__ __forceinline__ void xcd_barrier(const XcdBarrier& b) {
;     ...
;         const unsigned old = xb_add(&bar[XB_XSUB(b.x)], 1u);
;         const unsigned gen = old / nloc;
;         if (old + 1u == (gen + 1u) * nloc) {
;             __builtin_amdgcn_fence(__ATOMIC_RELEASE, "agent");
;             asm volatile("s_waitcnt vmcnt(0)" ::: "memory");
;             const unsigned og = xb_add(&bar[XB_TOP], 1u);
;             const unsigned tg = og / nx;
;             if (og + 1u == (tg + 1u) * nx) xb_add(&bar[XB_TOPGEN], 1u);
;             else XB_SPIN(xb_ld(&bar[XB_TOPGEN]) == tg, bar);
;             __builtin_amdgcn_fence(__ATOMIC_ACQUIRE, "agent");
;             xb_add(&bar[XB_XGEN(b.x)], 1u);
;             asm volatile("s_waitcnt vmcnt(0)" ::: "memory");
;         } else {
;             XB_SPIN(xb_ld(&bar[XB_XGEN(b.x)]) == gen, bar);
.LBB0_28:
	s_or_b64 exec, exec, s[4:5]
	v_cvt_f32_u32_e32 v6, v4
	s_waitcnt vmcnt(0)
	v_readfirstlane_b32 s4, v5
	v_sub_u32_e32 v5, 0, v4
	v_rcp_iflag_f32_e32 v6, v6
	v_add_u32_e32 v7, s4, v3
	v_mul_f32_e32 v6, 0x4f7ffffe, v6
	v_cvt_u32_f32_e32 v6, v6
	v_mul_lo_u32 v3, v5, v6
	v_mul_hi_u32 v3, v6, v3
	v_add_u32_e32 v3, v6, v3
	v_mul_hi_u32 v3, v7, v3
	v_mul_lo_u32 v5, v3, v4
	v_sub_u32_e32 v5, v7, v5
	v_add_u32_e32 v6, 1, v3
	v_cmp_ge_u32_e32 vcc, v5, v4
	s_nop 1
	v_cndmask_b32_e32 v3, v3, v6, vcc
	v_sub_u32_e32 v6, v5, v4
	v_cndmask_b32_e32 v5, v5, v6, vcc
	v_add_u32_e32 v6, 1, v3
	v_cmp_ge_u32_e32 vcc, v5, v4
	v_add_u32_e32 v5, 1, v7
	s_nop 0
	v_cndmask_b32_e32 v3, v3, v6, vcc
	v_mul_lo_u32 v6, v4, v3
	v_add_u32_e32 v4, v6, v4
	v_cmp_ne_u32_e32 vcc, v5, v4
	s_and_saveexec_b64 s[4:5], vcc
	s_xor_b64 s[4:5], exec, s[4:5]
	s_cbranch_execz .LBB0_42
	v_add_u32_e32 v3, 1, v3
	v_mul_lo_u32 v3, v3, v2
	v_readlane_b32 s28, v252, 26
	v_readlane_b32 s29, v252, 27
	s_waitcnt lgkmcnt(0)
	s_nop 3
	global_load_dword v2, v207, s[28:29] sc1
	s_waitcnt vmcnt(0)
	v_cmp_lt_u32_e32 vcc, v2, v3
	s_and_saveexec_b64 s[36:37], vcc
	s_cbranch_execz .LBB0_41
	s_mov_b32 s34, 1
	s_mov_b64 s[38:39], 0
	s_branch .LBB0_32

; __device__ __forceinline__ unsigned xb_ld(unsigned* p)              { return __hip_atomic_load(p, __ATOMIC_RELAXED, __HIP_MEMORY_SCOPE_AGENT); }
; #define XB_SPIN(cond, bar) do { unsigned _sp = 0; while (cond) { __builtin_amdgcn_s_sleep(1); \
;     if ((++_sp & 255u) == 0u) { if (xb_ld(&(bar)[XB_TMO])) break; if (_sp > XB_SPIN_CAP) { atomicAdd(&(bar)[XB_TMO], 1u); break; } } } } while (0)
; __device__ __forceinline__ void xcd_barrier(const XcdBarrier& b) {
;     ...
;             XB_SPIN(xb_ld(&bar[XB_XGEN(b.x)]) == gen, bar);
.LBB0_34:
	v_readlane_b32 s28, v252, 26
	v_readlane_b32 s29, v252, 27
	s_add_i32 s34, s34, 1
	s_mov_b64 s[44:45], -1
	s_nop 2
	global_load_dword v2, v207, s[28:29] sc1
	s_waitcnt vmcnt(0)
	v_cmp_ge_u32_e32 vcc, v2, v3
	s_orn2_b64 s[42:43], vcc, exec
	s_branch .LBB0_31

; __device__ __forceinline__ unsigned xb_ld(unsigned* p)              { return __hip_atomic_load(p, __ATOMIC_RELAXED, __HIP_MEMORY_SCOPE_AGENT); }
; __device__ __forceinline__ unsigned xb_add(unsigned* p, unsigned v) { return __hip_atomic_fetch_add(p, v, __ATOMIC_RELAXED, __HIP_MEMORY_SCOPE_AGENT); }
; #define XB_SPIN(cond, bar) do { unsigned _sp = 0; while (cond) { __builtin_amdgcn_s_sleep(1); \
;     if ((++_sp & 255u) == 0u) { if (xb_ld(&(bar)[XB_TMO])) break; if (_sp > XB_SPIN_CAP) { atomicAdd(&(bar)[XB_TMO], 1u); break; } } } } while (0)
; __device__ __forceinline__ void xcd_barrier(const XcdBarrier& b) {
;     ...
;             const unsigned og = xb_add(&bar[XB_TOP], 1u);
;             const unsigned tg = og / nx;
;             if (og + 1u == (tg + 1u) * nx) xb_add(&bar[XB_TOPGEN], 1u);
;             else XB_SPIN(xb_ld(&bar[XB_TOPGEN]) == tg, bar);
;             __builtin_amdgcn_fence(__ATOMIC_ACQUIRE, "agent");
;             xb_add(&bar[XB_XGEN(b.x)], 1u);
;             asm volatile("s_waitcnt vmcnt(0)" ::: "memory");
;         } else {
;             XB_SPIN(xb_ld(&bar[XB_XGEN(b.x)]) == gen, bar);
.LBB0_45:
	s_or_b64 exec, exec, s[36:37]
	v_cvt_f32_u32_e32 v5, v2
	s_waitcnt vmcnt(0)
	v_readfirstlane_b32 s4, v4
	s_mov_b64 s[36:37], -1
	v_rcp_iflag_f32_e32 v5, v5
	v_add_u32_e32 v3, s4, v3
	v_add_u32_e32 v6, 1, v3
	v_readlane_b32 s4, v252, 28
	v_mul_f32_e32 v4, 0x4f7ffffe, v5
	v_cvt_u32_f32_e32 v4, v4
	v_sub_u32_e32 v5, 0, v2
	v_readlane_b32 s5, v252, 29
	v_mul_lo_u32 v5, v5, v4
	v_mul_hi_u32 v5, v4, v5
	v_add_u32_e32 v4, v4, v5
	v_mul_hi_u32 v4, v3, v4
	v_mul_lo_u32 v5, v4, v2
	v_sub_u32_e32 v3, v3, v5
	v_add_u32_e32 v7, 1, v4
	v_cmp_ge_u32_e32 vcc, v3, v2
	v_sub_u32_e32 v5, v3, v2
	s_nop 0
	v_cndmask_b32_e32 v4, v4, v7, vcc
	v_cndmask_b32_e32 v3, v3, v5, vcc
	v_add_u32_e32 v5, 1, v4
	v_cmp_ge_u32_e32 vcc, v3, v2
	s_nop 1
	v_cndmask_b32_e32 v4, v4, v5, vcc
	v_mul_lo_u32 v3, v2, v4
	v_add_u32_e32 v2, v3, v2
	v_cmp_ne_u32_e32 vcc, v6, v2
	v_mov_b32_e32 v4, v2
	s_and_saveexec_b64 s[4:5], vcc
	s_cbranch_execz .LBB0_59
	v_readlane_b32 s28, v252, 26
	v_readlane_b32 s29, v252, 27
	s_mov_b64 s[38:39], 0
	s_nop 3
	global_load_dword v2, v207, s[28:29] sc1
	s_waitcnt vmcnt(0)
	v_cmp_lt_u32_e32 vcc, v2, v4
	s_and_saveexec_b64 s[36:37], vcc
	s_cbranch_execz .LBB0_56
	s_mov_b32 s34, 1
	s_branch .LBB0_49

; __device__ __forceinline__ unsigned xb_ld(unsigned* p)              { return __hip_atomic_load(p, __ATOMIC_RELAXED, __HIP_MEMORY_SCOPE_AGENT); }
; #define XB_SPIN(cond, bar) do { unsigned _sp = 0; while (cond) { __builtin_amdgcn_s_sleep(1); \
;     if ((++_sp & 255u) == 0u) { if (xb_ld(&(bar)[XB_TMO])) break; if (_sp > XB_SPIN_CAP) { atomicAdd(&(bar)[XB_TMO], 1u); break; } } } } while (0)
; __device__ __forceinline__ void xcd_barrier(const XcdBarrier& b) {
;     ...
;             else XB_SPIN(xb_ld(&bar[XB_TOPGEN]) == tg, bar);
.LBB0_51:
	v_readlane_b32 s28, v252, 26
	v_readlane_b32 s29, v252, 27
	s_add_i32 s34, s34, 1
	s_mov_b64 s[44:45], -1
	s_nop 2
	global_load_dword v2, v207, s[28:29] sc1
	s_waitcnt vmcnt(0)
	v_cmp_ge_u32_e32 vcc, v2, v4
	s_orn2_b64 s[42:43], vcc, exec
	s_branch .LBB0_48

; __device__ __forceinline__ unsigned xb_ld(unsigned* p)              { return __hip_atomic_load(p, __ATOMIC_RELAXED, __HIP_MEMORY_SCOPE_AGENT); }
; __device__ __forceinline__ unsigned xb_add(unsigned* p, unsigned v) { return __hip_atomic_fetch_add(p, v, __ATOMIC_RELAXED, __HIP_MEMORY_SCOPE_AGENT); }
; #define XB_SPIN(cond, bar) do { unsigned _sp = 0; while (cond) { __builtin_amdgcn_s_sleep(1); \
;     if ((++_sp & 255u) == 0u) { if (xb_ld(&(bar)[XB_TMO])) break; if (_sp > XB_SPIN_CAP) { atomicAdd(&(bar)[XB_TMO], 1u); break; } } } } while (0)
; __device__ __forceinline__ void xcd_barrier(const XcdBarrier& b) {
;     ...
;         const unsigned old = xb_add(&bar[XB_XSUB(b.x)], 1u);
;         const unsigned gen = old / nloc;
;         if (old + 1u == (gen + 1u) * nloc) {
;             __builtin_amdgcn_fence(__ATOMIC_RELEASE, "agent");
;             asm volatile("s_waitcnt vmcnt(0)" ::: "memory");
;             const unsigned og = xb_add(&bar[XB_TOP], 1u);
;             const unsigned tg = og / nx;
;             if (og + 1u == (tg + 1u) * nx) xb_add(&bar[XB_TOPGEN], 1u);
;             else XB_SPIN(xb_ld(&bar[XB_TOPGEN]) == tg, bar);
;             __builtin_amdgcn_fence(__ATOMIC_ACQUIRE, "agent");
;             xb_add(&bar[XB_XGEN(b.x)], 1u);
;             asm volatile("s_waitcnt vmcnt(0)" ::: "memory");
;         } else {
;             XB_SPIN(xb_ld(&bar[XB_XGEN(b.x)]) == gen, bar);
.LBB0_307:
	s_or_b64 exec, exec, s[4:5]
	v_cvt_f32_u32_e32 v6, v4
	s_waitcnt vmcnt(0)
	v_readfirstlane_b32 s4, v5
	v_sub_u32_e32 v5, 0, v4
	v_rcp_iflag_f32_e32 v6, v6
	v_add_u32_e32 v7, s4, v3
	v_mul_f32_e32 v6, 0x4f7ffffe, v6
	v_cvt_u32_f32_e32 v6, v6
	v_mul_lo_u32 v3, v5, v6
	v_mul_hi_u32 v3, v6, v3
	v_add_u32_e32 v3, v6, v3
	v_mul_hi_u32 v3, v7, v3
	v_mul_lo_u32 v5, v3, v4
	v_sub_u32_e32 v5, v7, v5
	v_add_u32_e32 v6, 1, v3
	v_cmp_ge_u32_e32 vcc, v5, v4
	s_nop 1
	v_cndmask_b32_e32 v3, v3, v6, vcc
	v_sub_u32_e32 v6, v5, v4
	v_cndmask_b32_e32 v5, v5, v6, vcc
	v_add_u32_e32 v6, 1, v3
	v_cmp_ge_u32_e32 vcc, v5, v4
	v_add_u32_e32 v5, 1, v7
	s_nop 0
	v_cndmask_b32_e32 v3, v3, v6, vcc
	v_mul_lo_u32 v6, v4, v3
	v_add_u32_e32 v4, v6, v4
	v_cmp_ne_u32_e32 vcc, v5, v4
	s_and_saveexec_b64 s[4:5], vcc
	s_xor_b64 s[4:5], exec, s[4:5]
	s_cbranch_execz .LBB0_321
	v_add_u32_e32 v3, 1, v3
	v_mul_lo_u32 v3, v3, v2
	v_readlane_b32 s28, v252, 26
	v_readlane_b32 s29, v252, 27
	s_waitcnt lgkmcnt(0)
	s_nop 3
	global_load_dword v2, v207, s[28:29] sc1
	s_waitcnt vmcnt(0)
	v_cmp_lt_u32_e32 vcc, v2, v3
	s_and_saveexec_b64 s[38:39], vcc
	s_cbranch_execz .LBB0_320
	s_mov_b32 s34, 1
	s_mov_b64 s[40:41], 0
	s_branch .LBB0_311

; __device__ __forceinline__ unsigned xb_ld(unsigned* p)              { return __hip_atomic_load(p, __ATOMIC_RELAXED, __HIP_MEMORY_SCOPE_AGENT); }
; #define XB_SPIN(cond, bar) do { unsigned _sp = 0; while (cond) { __builtin_amdgcn_s_sleep(1); \
;     if ((++_sp & 255u) == 0u) { if (xb_ld(&(bar)[XB_TMO])) break; if (_sp > XB_SPIN_CAP) { atomicAdd(&(bar)[XB_TMO], 1u); break; } } } } while (0)
; __device__ __forceinline__ void xcd_barrier(const XcdBarrier& b) {
;     ...
;             XB_SPIN(xb_ld(&bar[XB_XGEN(b.x)]) == gen, bar);
.LBB0_313:
	v_readlane_b32 s28, v252, 26
	v_readlane_b32 s29, v252, 27
	s_add_i32 s34, s34, 1
	s_mov_b64 s[48:49], -1
	s_nop 2
	global_load_dword v2, v207, s[28:29] sc1
	s_waitcnt vmcnt(0)
	v_cmp_ge_u32_e32 vcc, v2, v3
	s_orn2_b64 s[46:47], vcc, exec
	s_branch .LBB0_310

; __device__ __forceinline__ unsigned xb_ld(unsigned* p)              { return __hip_atomic_load(p, __ATOMIC_RELAXED, __HIP_MEMORY_SCOPE_AGENT); }
; __device__ __forceinline__ unsigned xb_add(unsigned* p, unsigned v) { return __hip_atomic_fetch_add(p, v, __ATOMIC_RELAXED, __HIP_MEMORY_SCOPE_AGENT); }
; #define XB_SPIN(cond, bar) do { unsigned _sp = 0; while (cond) { __builtin_amdgcn_s_sleep(1); \
;     if ((++_sp & 255u) == 0u) { if (xb_ld(&(bar)[XB_TMO])) break; if (_sp > XB_SPIN_CAP) { atomicAdd(&(bar)[XB_TMO], 1u); break; } } } } while (0)
; __device__ __forceinline__ void xcd_barrier(const XcdBarrier& b) {
;     ...
;             const unsigned og = xb_add(&bar[XB_TOP], 1u);
;             const unsigned tg = og / nx;
;             if (og + 1u == (tg + 1u) * nx) xb_add(&bar[XB_TOPGEN], 1u);
;             else XB_SPIN(xb_ld(&bar[XB_TOPGEN]) == tg, bar);
;             __builtin_amdgcn_fence(__ATOMIC_ACQUIRE, "agent");
;             xb_add(&bar[XB_XGEN(b.x)], 1u);
;             asm volatile("s_waitcnt vmcnt(0)" ::: "memory");
;         } else {
;             XB_SPIN(xb_ld(&bar[XB_XGEN(b.x)]) == gen, bar);
.LBB0_324:
	s_or_b64 exec, exec, s[38:39]
	s_waitcnt vmcnt(0)
	v_readfirstlane_b32 s4, v4
	v_cvt_f32_u32_e32 v4, v2
	v_sub_u32_e32 v5, 0, v2
	v_add_u32_e32 v3, s4, v3
	v_readlane_b32 s4, v252, 28
	v_rcp_iflag_f32_e32 v4, v4
	v_readlane_b32 s5, v252, 29
	s_mov_b64 s[38:39], -1
	v_mul_f32_e32 v4, 0x4f7ffffe, v4
	v_cvt_u32_f32_e32 v4, v4
	v_mul_lo_u32 v5, v5, v4
	v_mul_hi_u32 v5, v4, v5
	v_add_u32_e32 v4, v4, v5
	v_mul_hi_u32 v4, v3, v4
	v_mul_lo_u32 v5, v4, v2
	v_sub_u32_e32 v5, v3, v5
	v_cmp_ge_u32_e32 vcc, v5, v2
	v_add_u32_e32 v6, 1, v4
	v_add_u32_e32 v3, 1, v3
	v_cndmask_b32_e32 v4, v4, v6, vcc
	v_sub_u32_e32 v6, v5, v2
	v_cndmask_b32_e32 v5, v5, v6, vcc
	v_cmp_ge_u32_e32 vcc, v5, v2
	v_add_u32_e32 v5, 1, v4
	s_nop 0
	v_cndmask_b32_e32 v4, v4, v5, vcc
	v_mul_lo_u32 v5, v2, v4
	v_add_u32_e32 v2, v5, v2
	v_cmp_ne_u32_e32 vcc, v3, v2
	v_mov_b32_e32 v4, v2
	s_and_saveexec_b64 s[4:5], vcc
	s_cbranch_execz .LBB0_338
	v_readlane_b32 s28, v252, 26
	v_readlane_b32 s29, v252, 27
	s_mov_b64 s[40:41], 0
	s_nop 3
	global_load_dword v2, v207, s[28:29] sc1
	s_waitcnt vmcnt(0)
	v_cmp_lt_u32_e32 vcc, v2, v4
	s_and_saveexec_b64 s[38:39], vcc
	s_cbranch_execz .LBB0_335
	s_mov_b32 s34, 1
	s_branch .LBB0_328

; __device__ __forceinline__ unsigned xb_ld(unsigned* p)              { return __hip_atomic_load(p, __ATOMIC_RELAXED, __HIP_MEMORY_SCOPE_AGENT); }
; #define XB_SPIN(cond, bar) do { unsigned _sp = 0; while (cond) { __builtin_amdgcn_s_sleep(1); \
;     if ((++_sp & 255u) == 0u) { if (xb_ld(&(bar)[XB_TMO])) break; if (_sp > XB_SPIN_CAP) { atomicAdd(&(bar)[XB_TMO], 1u); break; } } } } while (0)
; __device__ __forceinline__ void xcd_barrier(const XcdBarrier& b) {
;     ...
;             else XB_SPIN(xb_ld(&bar[XB_TOPGEN]) == tg, bar);
.LBB0_330:
	v_readlane_b32 s28, v252, 26
	v_readlane_b32 s29, v252, 27
	s_add_i32 s34, s34, 1
	s_mov_b64 s[48:49], -1
	s_nop 2
	global_load_dword v2, v207, s[28:29] sc1
	s_waitcnt vmcnt(0)
	v_cmp_ge_u32_e32 vcc, v2, v4
	s_orn2_b64 s[46:47], vcc, exec
	s_branch .LBB0_327

; __device__ __forceinline__ unsigned xb_ld(unsigned* p)              { return __hip_atomic_load(p, __ATOMIC_RELAXED, __HIP_MEMORY_SCOPE_AGENT); }
; __device__ __forceinline__ unsigned xb_add(unsigned* p, unsigned v) { return __hip_atomic_fetch_add(p, v, __ATOMIC_RELAXED, __HIP_MEMORY_SCOPE_AGENT); }
; #define XB_SPIN(cond, bar) do { unsigned _sp = 0; while (cond) { __builtin_amdgcn_s_sleep(1); \
;     if ((++_sp & 255u) == 0u) { if (xb_ld(&(bar)[XB_TMO])) break; if (_sp > XB_SPIN_CAP) { atomicAdd(&(bar)[XB_TMO], 1u); break; } } } } while (0)
; __device__ __forceinline__ void xcd_barrier(const XcdBarrier& b) {
;     ...
;             const unsigned og = xb_add(&bar[XB_TOP], 1u);
;             const unsigned tg = og / nx;
;             if (og + 1u == (tg + 1u) * nx) xb_add(&bar[XB_TOPGEN], 1u);
;             else XB_SPIN(xb_ld(&bar[XB_TOPGEN]) == tg, bar);
;             __builtin_amdgcn_fence(__ATOMIC_ACQUIRE, "agent");
;             xb_add(&bar[XB_XGEN(b.x)], 1u);
;             asm volatile("s_waitcnt vmcnt(0)" ::: "memory");
;         } else {
;             XB_SPIN(xb_ld(&bar[XB_XGEN(b.x)]) == gen, bar);
.LBB0_961:
	s_or_b64 exec, exec, s[36:37]
	s_waitcnt vmcnt(0)
	v_readfirstlane_b32 s4, v4
	v_cvt_f32_u32_e32 v4, v2
	v_sub_u32_e32 v5, 0, v2
	v_add_u32_e32 v3, s4, v3
	v_readlane_b32 s4, v252, 28
	v_rcp_iflag_f32_e32 v4, v4
	v_readlane_b32 s5, v252, 29
	s_mov_b64 s[36:37], -1
	v_mul_f32_e32 v4, 0x4f7ffffe, v4
	v_cvt_u32_f32_e32 v4, v4
	v_mul_lo_u32 v5, v5, v4
	v_mul_hi_u32 v5, v4, v5
	v_add_u32_e32 v4, v4, v5
	v_mul_hi_u32 v4, v3, v4
	v_mul_lo_u32 v5, v4, v2
	v_sub_u32_e32 v5, v3, v5
	v_cmp_ge_u32_e32 vcc, v5, v2
	v_add_u32_e32 v6, 1, v4
	v_add_u32_e32 v3, 1, v3
	v_cndmask_b32_e32 v4, v4, v6, vcc
	v_sub_u32_e32 v6, v5, v2
	v_cndmask_b32_e32 v5, v5, v6, vcc
	v_cmp_ge_u32_e32 vcc, v5, v2
	v_add_u32_e32 v5, 1, v4
	s_nop 0
	v_cndmask_b32_e32 v4, v4, v5, vcc
	v_mul_lo_u32 v5, v2, v4
	v_add_u32_e32 v2, v5, v2
	v_cmp_ne_u32_e32 vcc, v3, v2
	v_mov_b32_e32 v4, v2
	s_and_saveexec_b64 s[4:5], vcc
	s_cbranch_execz .LBB0_975
	v_readlane_b32 s28, v252, 26
	v_readlane_b32 s29, v252, 27
	s_mov_b64 s[38:39], 0
	s_nop 3
	global_load_dword v2, v207, s[28:29] sc1
	s_waitcnt vmcnt(0)
	v_cmp_lt_u32_e32 vcc, v2, v4
	s_and_saveexec_b64 s[36:37], vcc
	s_cbranch_execz .LBB0_972
	s_mov_b32 s34, 1
	s_branch .LBB0_965
